# P2/P8 unit loops: the 128 accumulators are cleared with 64 v_mov_b64 instead of 128 v_mov_b32
# baseline (speedup 1.0000x reference)
; template <class Epi, class Sched, bool ALIGN_EPI = false, bool SP2 = false>
; __device__ __forceinline__ void gemm_phase(PG8_LAS unsigned char* lds, const Gemm g, const Sched& S, const Epi& E) {
;     ...
;         const bool has_next = S.next(ui + 1, nxt);
;         const char* nA = has_next ? (const char*)g.A + (size_t)nxt.pm * tstep : cA; const char* nB = has_next ? (const char*)g.Bt + (size_t)nxt.pn * tstep : cB;
;     ...
; #pragma unroll
;         for (int a = 0; a < 2; ++a)
; #pragma unroll
;             for (int b = 0; b < 2; ++b)
; #pragma unroll
;                 for (int m = 0; m < 4; ++m)
; #pragma unroll
;                     for (int n = 0; n < 2; ++n) acc[a][b][m][n] = (f32x4){0.f, 0.f, 0.f, 0.f};
;         cur = nxt; cA = nA; cB = nB; ++ui;
.LBB0_269:
	s_ashr_i32 s81, s80, 31
	s_lshl_b64 s[0:1], s[80:81], 19
	s_add_u32 s82, s76, s0
	s_addc_u32 s83, s77, s1
	s_and_b64 s[0:1], s[4:5], exec
	s_cselect_b32 s0, s83, s89
	s_cselect_b32 s1, s82, s88
	s_ashr_i32 s69, s68, 31
	s_lshl_b64 s[84:85], s[68:69], 19
	s_add_u32 s84, s8, s84
	s_addc_u32 s85, s9, s85
	s_and_b64 s[92:93], s[4:5], exec
	s_cselect_b32 s7, s85, s91
	s_cselect_b32 s69, s84, s90
	s_add_u32 s88, s88, 0x40080
	s_addc_u32 s89, s89, 0
	s_add_u32 s81, s90, 0x100
	v_mov_b32_e32 v2, 0
	s_addc_u32 s87, s91, 0
	s_mov_b32 s96, -2
	v_mov_b32_e32 v3, 0
	v_mov_b64_e32 v[4:5], v[2:3]
	v_mov_b64_e32 v[6:7], v[2:3]
	v_mov_b64_e32 v[8:9], v[2:3]
	v_mov_b64_e32 v[10:11], v[2:3]
	v_mov_b64_e32 v[12:13], v[2:3]
	v_mov_b64_e32 v[14:15], v[2:3]
	v_mov_b64_e32 v[16:17], v[2:3]
	v_mov_b64_e32 v[18:19], v[2:3]
	v_mov_b64_e32 v[20:21], v[2:3]
	v_mov_b64_e32 v[22:23], v[2:3]
	v_mov_b64_e32 v[24:25], v[2:3]
	v_mov_b64_e32 v[26:27], v[2:3]
	v_mov_b64_e32 v[28:29], v[2:3]
	v_mov_b64_e32 v[30:31], v[2:3]
	v_mov_b64_e32 v[32:33], v[2:3]
	v_mov_b64_e32 v[34:35], v[2:3]
	v_mov_b64_e32 v[36:37], v[2:3]
	v_mov_b64_e32 v[38:39], v[2:3]
	v_mov_b64_e32 v[40:41], v[2:3]
	v_mov_b64_e32 v[42:43], v[2:3]
	v_mov_b64_e32 v[44:45], v[2:3]
	v_mov_b64_e32 v[46:47], v[2:3]
	v_mov_b64_e32 v[48:49], v[2:3]
	v_mov_b64_e32 v[50:51], v[2:3]
	v_mov_b64_e32 v[52:53], v[2:3]
	v_mov_b64_e32 v[54:55], v[2:3]
	v_mov_b64_e32 v[56:57], v[2:3]
	v_mov_b64_e32 v[58:59], v[2:3]
	v_mov_b64_e32 v[60:61], v[2:3]
	v_mov_b64_e32 v[62:63], v[2:3]
	v_mov_b64_e32 v[64:65], v[2:3]
	v_mov_b64_e32 v[66:67], v[2:3]
	v_mov_b64_e32 v[68:69], v[2:3]
	v_mov_b64_e32 v[70:71], v[2:3]
	v_mov_b64_e32 v[72:73], v[2:3]
	v_mov_b64_e32 v[74:75], v[2:3]
	v_mov_b64_e32 v[76:77], v[2:3]
	v_mov_b64_e32 v[78:79], v[2:3]
	v_mov_b64_e32 v[80:81], v[2:3]
	v_mov_b64_e32 v[82:83], v[2:3]
	v_mov_b64_e32 v[84:85], v[2:3]
	v_mov_b64_e32 v[86:87], v[2:3]
	v_mov_b64_e32 v[88:89], v[2:3]
	v_mov_b64_e32 v[90:91], v[2:3]
	v_mov_b64_e32 v[92:93], v[2:3]
	v_mov_b64_e32 v[94:95], v[2:3]
	v_mov_b64_e32 v[96:97], v[2:3]
	v_mov_b64_e32 v[98:99], v[2:3]
	v_mov_b64_e32 v[100:101], v[2:3]
	v_mov_b64_e32 v[102:103], v[2:3]
	v_mov_b64_e32 v[104:105], v[2:3]
	v_mov_b64_e32 v[106:107], v[2:3]
	v_mov_b64_e32 v[108:109], v[2:3]
	v_mov_b64_e32 v[110:111], v[2:3]
	v_mov_b64_e32 v[112:113], v[2:3]
	v_mov_b64_e32 v[114:115], v[2:3]
	v_mov_b64_e32 v[116:117], v[2:3]
	v_mov_b64_e32 v[118:119], v[2:3]
	v_mov_b64_e32 v[120:121], v[2:3]
	v_mov_b64_e32 v[122:123], v[2:3]
	v_mov_b64_e32 v[124:125], v[2:3]
	v_mov_b64_e32 v[126:127], v[2:3]
	v_mov_b64_e32 v[128:129], v[2:3]

; template <class Epi, class Sched, bool ALIGN_EPI = false, bool SP2 = false>
; __device__ __forceinline__ void gemm_phase(PG8_LAS unsigned char* lds, const Gemm g, const Sched& S, const Epi& E) {
;     ...
;         const bool has_next = S.next(ui + 1, nxt);
;         const char* nA = has_next ? (const char*)g.A + (size_t)nxt.pm * tstep : cA; const char* nB = has_next ? (const char*)g.Bt + (size_t)nxt.pn * tstep : cB;
;     ...
; #pragma unroll
;         for (int a = 0; a < 2; ++a)
; #pragma unroll
;             for (int b = 0; b < 2; ++b)
; #pragma unroll
;                 for (int m = 0; m < 4; ++m)
; #pragma unroll
;                     for (int n = 0; n < 2; ++n) acc[a][b][m][n] = (f32x4){0.f, 0.f, 0.f, 0.f};
;         cur = nxt; cA = nA; cB = nB; ++ui;
.LBB0_1174:
	s_ashr_i32 s27, s26, 31
	s_lshl_b64 s[0:1], s[26:27], 19
	s_add_u32 s30, s20, s0
	s_addc_u32 s31, s21, s1
	s_and_b64 s[0:1], s[4:5], exec
	s_cselect_b32 s0, s31, s41
	s_cselect_b32 s1, s30, s40
	s_ashr_i32 s29, s28, 31
	s_lshl_b64 s[36:37], s[28:29], 19
	s_add_u32 s36, s24, s36
	s_addc_u32 s37, s25, s37
	s_and_b64 s[44:45], s[4:5], exec
	s_cselect_b32 s27, s37, s43
	s_cselect_b32 s29, s36, s42
	s_add_u32 s40, s40, 0x40080
	s_addc_u32 s41, s41, 0
	s_add_u32 s53, s42, 0x100
	v_mov_b32_e32 v2, 0
	s_addc_u32 s54, s43, 0
	s_mov_b32 s55, -2
	v_mov_b32_e32 v3, 0
	v_mov_b64_e32 v[4:5], v[2:3]
	v_mov_b64_e32 v[6:7], v[2:3]
	v_mov_b64_e32 v[8:9], v[2:3]
	v_mov_b64_e32 v[10:11], v[2:3]
	v_mov_b64_e32 v[12:13], v[2:3]
	v_mov_b64_e32 v[14:15], v[2:3]
	v_mov_b64_e32 v[16:17], v[2:3]
	v_mov_b64_e32 v[18:19], v[2:3]
	v_mov_b64_e32 v[20:21], v[2:3]
	v_mov_b64_e32 v[22:23], v[2:3]
	v_mov_b64_e32 v[24:25], v[2:3]
	v_mov_b64_e32 v[26:27], v[2:3]
	v_mov_b64_e32 v[28:29], v[2:3]
	v_mov_b64_e32 v[30:31], v[2:3]
	v_mov_b64_e32 v[32:33], v[2:3]
	v_mov_b64_e32 v[34:35], v[2:3]
	v_mov_b64_e32 v[36:37], v[2:3]
	v_mov_b64_e32 v[38:39], v[2:3]
	v_mov_b64_e32 v[40:41], v[2:3]
	v_mov_b64_e32 v[42:43], v[2:3]
	v_mov_b64_e32 v[44:45], v[2:3]
	v_mov_b64_e32 v[46:47], v[2:3]
	v_mov_b64_e32 v[48:49], v[2:3]
	v_mov_b64_e32 v[50:51], v[2:3]
	v_mov_b64_e32 v[52:53], v[2:3]
	v_mov_b64_e32 v[54:55], v[2:3]
	v_mov_b64_e32 v[56:57], v[2:3]
	v_mov_b64_e32 v[58:59], v[2:3]
	v_mov_b64_e32 v[60:61], v[2:3]
	v_mov_b64_e32 v[62:63], v[2:3]
	v_mov_b64_e32 v[64:65], v[2:3]
	v_mov_b64_e32 v[66:67], v[2:3]
	v_mov_b64_e32 v[68:69], v[2:3]
	v_mov_b64_e32 v[70:71], v[2:3]
	v_mov_b64_e32 v[72:73], v[2:3]
	v_mov_b64_e32 v[74:75], v[2:3]
	v_mov_b64_e32 v[76:77], v[2:3]
	v_mov_b64_e32 v[78:79], v[2:3]
	v_mov_b64_e32 v[80:81], v[2:3]
	v_mov_b64_e32 v[82:83], v[2:3]
	v_mov_b64_e32 v[84:85], v[2:3]
	v_mov_b64_e32 v[86:87], v[2:3]
	v_mov_b64_e32 v[88:89], v[2:3]
	v_mov_b64_e32 v[90:91], v[2:3]
	v_mov_b64_e32 v[92:93], v[2:3]
	v_mov_b64_e32 v[94:95], v[2:3]
	v_mov_b64_e32 v[96:97], v[2:3]
	v_mov_b64_e32 v[98:99], v[2:3]
	v_mov_b64_e32 v[100:101], v[2:3]
	v_mov_b64_e32 v[102:103], v[2:3]
	v_mov_b64_e32 v[104:105], v[2:3]
	v_mov_b64_e32 v[106:107], v[2:3]
	v_mov_b64_e32 v[108:109], v[2:3]
	v_mov_b64_e32 v[110:111], v[2:3]
	v_mov_b64_e32 v[112:113], v[2:3]
	v_mov_b64_e32 v[114:115], v[2:3]
	v_mov_b64_e32 v[116:117], v[2:3]
	v_mov_b64_e32 v[118:119], v[2:3]
	v_mov_b64_e32 v[120:121], v[2:3]
	v_mov_b64_e32 v[122:123], v[2:3]
	v_mov_b64_e32 v[124:125], v[2:3]
	v_mov_b64_e32 v[126:127], v[2:3]
	v_mov_b64_e32 v[128:129], v[2:3]
